# load-segment instruction diet (SGPR-base LDS-DMA addressing, no s_nop / VALU address adds / setprio flips) now also on the up-projection GEMM loop, replacing its 4+4 stage rebalance
# baseline (speedup 1.0000x reference)
.LBB0_68:
	s_add_u32 s8, s6, 0xfff80080
	s_addc_u32 s9, s7, -1
	s_cmp_eq_u32 s51, 28
	s_cselect_b32 s11, s21, s9
	s_cselect_b32 s10, s28, s8
	s_cselect_b32 s9, s19, s31
	s_cselect_b32 s8, s29, s30
	v_add_u32_e32 v16, 0x10000, v190
	ds_read_b128 v[54:57], v16
	ds_read_b128 v[62:65], v16 offset:1024
	ds_read_b128 v[66:69], v16 offset:2048
	ds_read_b128 v[70:73], v16 offset:3072
	v_add_u32_e32 v16, 0x14000, v190
	ds_read_b128 v[74:77], v16
	ds_read_b128 v[78:81], v16 offset:1024
	ds_read_b128 v[82:85], v16 offset:2048
	ds_read_b128 v[86:89], v16 offset:3072
	ds_read_b128 v[170:173], v192
	ds_read_b128 v[184:187], v192 offset:1024
	ds_read_b128 v[194:197], v192 offset:2048
	ds_read_b128 v[198:201], v192 offset:3072
	ds_read_b128 v[202:205], v192 offset:4096
	s_add_i32 m0, s41, 0xc000
	ds_read_b128 v[206:209], v192 offset:5120
	global_load_lds_dwordx4 v180, s[6:7]
	s_add_i32 m0, s41, 0xe000
	ds_read_b128 v[210:213], v192 offset:6144
	global_load_lds_dwordx4 v182, s[6:7]
	ds_read_b128 v[222:225], v192 offset:7168
	s_waitcnt vmcnt(8)
	s_waitcnt lgkmcnt(0)
	s_barrier
	v_mfma_f32_16x16x32_bf16 v[150:153], v[54:57], v[170:173], v[150:153]
	v_mfma_f32_16x16x32_bf16 v[142:145], v[66:69], v[170:173], v[142:145]
	v_mfma_f32_16x16x32_bf16 v[134:137], v[54:57], v[194:197], v[134:137]
	v_mfma_f32_16x16x32_bf16 v[126:129], v[66:69], v[194:197], v[126:129]
	v_mfma_f32_16x16x32_bf16 v[118:121], v[54:57], v[202:205], v[118:121]
	v_mfma_f32_16x16x32_bf16 v[114:117], v[66:69], v[202:205], v[114:117]
	v_mfma_f32_16x16x32_bf16 v[110:113], v[54:57], v[210:213], v[110:113]
	v_mfma_f32_16x16x32_bf16 v[106:109], v[66:69], v[210:213], v[106:109]
	v_mfma_f32_16x16x32_bf16 v[150:153], v[62:65], v[184:187], v[150:153]
	v_mfma_f32_16x16x32_bf16 v[142:145], v[70:73], v[184:187], v[142:145]
	v_mfma_f32_16x16x32_bf16 v[134:137], v[62:65], v[198:201], v[134:137]
	v_mfma_f32_16x16x32_bf16 v[126:129], v[70:73], v[198:201], v[126:129]
	v_mfma_f32_16x16x32_bf16 v[118:121], v[62:65], v[206:209], v[118:121]
	v_mfma_f32_16x16x32_bf16 v[114:117], v[70:73], v[206:209], v[114:117]
	v_mfma_f32_16x16x32_bf16 v[110:113], v[62:65], v[222:225], v[110:113]
	v_mfma_f32_16x16x32_bf16 v[106:109], v[70:73], v[222:225], v[106:109]
	v_mfma_f32_16x16x32_bf16 v[158:161], v[74:77], v[170:173], v[158:161]
	v_mfma_f32_16x16x32_bf16 v[154:157], v[82:85], v[170:173], v[154:157]
	v_mfma_f32_16x16x32_bf16 v[146:149], v[74:77], v[194:197], v[146:149]
	v_mfma_f32_16x16x32_bf16 v[138:141], v[82:85], v[194:197], v[138:141]
	v_mfma_f32_16x16x32_bf16 v[130:133], v[74:77], v[202:205], v[130:133]
	v_mfma_f32_16x16x32_bf16 v[122:125], v[82:85], v[202:205], v[122:125]
	v_mfma_f32_16x16x32_bf16 v[102:105], v[74:77], v[210:213], v[102:105]
	v_mfma_f32_16x16x32_bf16 v[98:101], v[82:85], v[210:213], v[98:101]
	v_mfma_f32_16x16x32_bf16 v[158:161], v[78:81], v[184:187], v[158:161]
	v_mfma_f32_16x16x32_bf16 v[154:157], v[86:89], v[184:187], v[154:157]
	v_mfma_f32_16x16x32_bf16 v[146:149], v[78:81], v[198:201], v[146:149]
	v_mfma_f32_16x16x32_bf16 v[138:141], v[86:89], v[198:201], v[138:141]
	v_mfma_f32_16x16x32_bf16 v[130:133], v[78:81], v[206:209], v[130:133]
	v_mfma_f32_16x16x32_bf16 v[122:125], v[86:89], v[206:209], v[122:125]
	v_mfma_f32_16x16x32_bf16 v[102:105], v[78:81], v[222:225], v[102:105]
	v_mfma_f32_16x16x32_bf16 v[98:101], v[86:89], v[222:225], v[98:101]
	s_barrier
	ds_read_b128 v[170:173], v192 offset:16384
	s_add_i32 m0, s38, 0x10000
	ds_read_b128 v[184:187], v192 offset:17408
	global_load_lds_dwordx4 v166, s[8:9]
	s_add_i32 m0, s38, 0x12000
	s_add_u32 s52, s8, 0x80000
	s_addc_u32 s53, s9, 0
	ds_read_b128 v[194:197], v192 offset:18432
	global_load_lds_dwordx4 v162, s[8:9]
	s_add_i32 m0, s38, 0x14000
	ds_read_b128 v[198:201], v192 offset:19456
	global_load_lds_dwordx4 v166, s[52:53]
	s_add_i32 m0, s38, 0x16000
	ds_read_b128 v[202:205], v192 offset:20480
	global_load_lds_dwordx4 v162, s[52:53]
	s_mov_b32 m0, s41
	ds_read_b128 v[206:209], v192 offset:21504
	global_load_lds_dwordx4 v168, s[10:11]
	s_mov_b32 m0, s42
	ds_read_b128 v[210:213], v192 offset:22528
	global_load_lds_dwordx4 v164, s[10:11]
	ds_read_b128 v[222:225], v192 offset:23552
	s_waitcnt vmcnt(8)
	s_waitcnt lgkmcnt(0)
	s_barrier
	v_mfma_f32_16x16x32_bf16 v[58:61], v[54:57], v[170:173], v[58:61]
	v_mfma_f32_16x16x32_bf16 v[46:49], v[66:69], v[170:173], v[46:49]
	v_mfma_f32_16x16x32_bf16 v[38:41], v[54:57], v[194:197], v[38:41]
	v_mfma_f32_16x16x32_bf16 v[30:33], v[66:69], v[194:197], v[30:33]
	v_mfma_f32_16x16x32_bf16 v[22:25], v[54:57], v[202:205], v[22:25]
	v_mfma_f32_16x16x32_bf16 v[18:21], v[66:69], v[202:205], v[18:21]
	v_mfma_f32_16x16x32_bf16 v[8:11], v[54:57], v[210:213], v[8:11]
	v_mfma_f32_16x16x32_bf16 v[12:15], v[66:69], v[210:213], v[12:15]
	v_mfma_f32_16x16x32_bf16 v[58:61], v[62:65], v[184:187], v[58:61]
	v_mfma_f32_16x16x32_bf16 v[46:49], v[70:73], v[184:187], v[46:49]
	v_mfma_f32_16x16x32_bf16 v[38:41], v[62:65], v[198:201], v[38:41]
	v_mfma_f32_16x16x32_bf16 v[30:33], v[70:73], v[198:201], v[30:33]
	v_mfma_f32_16x16x32_bf16 v[22:25], v[62:65], v[206:209], v[22:25]
	v_mfma_f32_16x16x32_bf16 v[18:21], v[70:73], v[206:209], v[18:21]
	v_mfma_f32_16x16x32_bf16 v[8:11], v[62:65], v[222:225], v[8:11]
	v_mfma_f32_16x16x32_bf16 v[12:15], v[70:73], v[222:225], v[12:15]
	v_mfma_f32_16x16x32_bf16 v[50:53], v[74:77], v[194:197], v[50:53]
	v_mfma_f32_16x16x32_bf16 v[42:45], v[82:85], v[194:197], v[42:45]
	v_mfma_f32_16x16x32_bf16 v[34:37], v[74:77], v[202:205], v[34:37]
	v_mfma_f32_16x16x32_bf16 v[26:29], v[82:85], v[202:205], v[26:29]
	v_mfma_f32_16x16x32_bf16 v[0:3], v[74:77], v[210:213], v[0:3]
	v_mfma_f32_16x16x32_bf16 v[4:7], v[82:85], v[210:213], v[4:7]
	v_mfma_f32_16x16x32_bf16 v[54:57], v[74:77], v[170:173], v[94:97]
	v_mfma_f32_16x16x32_bf16 v[62:65], v[82:85], v[170:173], v[90:93]
	v_mfma_f32_16x16x32_bf16 v[50:53], v[78:81], v[198:201], v[50:53]
	v_mfma_f32_16x16x32_bf16 v[42:45], v[86:89], v[198:201], v[42:45]
	v_mfma_f32_16x16x32_bf16 v[34:37], v[78:81], v[206:209], v[34:37]
	v_mfma_f32_16x16x32_bf16 v[26:29], v[86:89], v[206:209], v[26:29]
	v_mfma_f32_16x16x32_bf16 v[0:3], v[78:81], v[222:225], v[0:3]
	v_mfma_f32_16x16x32_bf16 v[4:7], v[86:89], v[222:225], v[4:7]
	v_mfma_f32_16x16x32_bf16 v[54:57], v[78:81], v[184:187], v[54:57]
	v_mfma_f32_16x16x32_bf16 v[62:65], v[86:89], v[184:187], v[62:65]
	s_barrier
	s_add_u32 s100, s10, 0x80000
	s_addc_u32 s101, s11, 0
	v_add_u32_e32 v16, 0x18000, v190
	ds_read_b128 v[66:69], v16
	ds_read_b128 v[70:73], v16 offset:1024
	ds_read_b128 v[74:77], v16 offset:2048
	ds_read_b128 v[78:81], v16 offset:3072
	v_add_u32_e32 v16, 0x1c000, v190
	ds_read_b128 v[82:85], v16
	ds_read_b128 v[86:89], v16 offset:1024
	ds_read_b128 v[170:173], v16 offset:2048
	ds_read_b128 v[184:187], v16 offset:3072
	ds_read_b128 v[90:93], v192 offset:32768
	ds_read_b128 v[94:97], v192 offset:33792
	ds_read_b128 v[194:197], v192 offset:34816
	ds_read_b128 v[198:201], v192 offset:35840
	ds_read_b128 v[202:205], v192 offset:36864
	s_mov_b32 m0, s43
	ds_read_b128 v[206:209], v192 offset:37888
	global_load_lds_dwordx4 v168, s[100:101]
	s_mov_b32 m0, s44
	ds_read_b128 v[210:213], v192 offset:38912
	global_load_lds_dwordx4 v164, s[100:101]
	ds_read_b128 v[222:225], v192 offset:39936
	s_waitcnt vmcnt(8)
	s_waitcnt lgkmcnt(0)
	s_barrier
	v_mfma_f32_16x16x32_bf16 v[150:153], v[66:69], v[90:93], v[150:153]
	v_mfma_f32_16x16x32_bf16 v[142:145], v[74:77], v[90:93], v[142:145]
	v_mfma_f32_16x16x32_bf16 v[134:137], v[66:69], v[194:197], v[134:137]
	v_mfma_f32_16x16x32_bf16 v[126:129], v[74:77], v[194:197], v[126:129]
	v_mfma_f32_16x16x32_bf16 v[118:121], v[66:69], v[202:205], v[118:121]
	v_mfma_f32_16x16x32_bf16 v[114:117], v[74:77], v[202:205], v[114:117]
	v_mfma_f32_16x16x32_bf16 v[110:113], v[66:69], v[210:213], v[110:113]
	v_mfma_f32_16x16x32_bf16 v[106:109], v[74:77], v[210:213], v[106:109]
	v_mfma_f32_16x16x32_bf16 v[150:153], v[70:73], v[94:97], v[150:153]
	v_mfma_f32_16x16x32_bf16 v[142:145], v[78:81], v[94:97], v[142:145]
	v_mfma_f32_16x16x32_bf16 v[134:137], v[70:73], v[198:201], v[134:137]
	v_mfma_f32_16x16x32_bf16 v[126:129], v[78:81], v[198:201], v[126:129]
	v_mfma_f32_16x16x32_bf16 v[118:121], v[70:73], v[206:209], v[118:121]
	v_mfma_f32_16x16x32_bf16 v[114:117], v[78:81], v[206:209], v[114:117]
	v_mfma_f32_16x16x32_bf16 v[110:113], v[70:73], v[222:225], v[110:113]
	v_mfma_f32_16x16x32_bf16 v[106:109], v[78:81], v[222:225], v[106:109]
	v_mfma_f32_16x16x32_bf16 v[158:161], v[82:85], v[90:93], v[158:161]
	v_mfma_f32_16x16x32_bf16 v[90:93], v[170:173], v[90:93], v[154:157]
	v_mfma_f32_16x16x32_bf16 v[154:157], v[184:187], v[94:97], v[90:93]
	v_mfma_f32_16x16x32_bf16 v[90:93], v[82:85], v[194:197], v[146:149]
	v_mfma_f32_16x16x32_bf16 v[146:149], v[86:89], v[198:201], v[90:93]
	v_mfma_f32_16x16x32_bf16 v[90:93], v[170:173], v[194:197], v[138:141]
	v_mfma_f32_16x16x32_bf16 v[138:141], v[184:187], v[198:201], v[90:93]
	v_mfma_f32_16x16x32_bf16 v[90:93], v[82:85], v[202:205], v[130:133]
	v_mfma_f32_16x16x32_bf16 v[130:133], v[86:89], v[206:209], v[90:93]
	v_mfma_f32_16x16x32_bf16 v[90:93], v[170:173], v[202:205], v[122:125]
	v_mfma_f32_16x16x32_bf16 v[122:125], v[184:187], v[206:209], v[90:93]
	v_mfma_f32_16x16x32_bf16 v[90:93], v[82:85], v[210:213], v[102:105]
	v_mfma_f32_16x16x32_bf16 v[102:105], v[86:89], v[222:225], v[90:93]
	v_mfma_f32_16x16x32_bf16 v[90:93], v[170:173], v[210:213], v[98:101]
	v_mfma_f32_16x16x32_bf16 v[158:161], v[86:89], v[94:97], v[158:161]
	v_mfma_f32_16x16x32_bf16 v[98:101], v[184:187], v[222:225], v[90:93]
	s_barrier
	ds_read_b128 v[90:93], v192 offset:49152
	s_add_i32 m0, s38, 0x17f80
	ds_read_b128 v[194:197], v192 offset:50176
	global_load_lds_dwordx4 v166, s[8:9] offset:128
	s_add_i32 m0, s38, 0x19f80
	ds_read_b128 v[198:201], v192 offset:51200
	global_load_lds_dwordx4 v162, s[8:9] offset:128
	s_add_i32 m0, s38, 0x1bf80
	ds_read_b128 v[202:205], v192 offset:52224
	global_load_lds_dwordx4 v166, s[52:53] offset:128
	s_add_i32 m0, s38, 0x1df80
	ds_read_b128 v[206:209], v192 offset:53248
	global_load_lds_dwordx4 v162, s[52:53] offset:128
	s_add_i32 m0, s46, 0xffffff80
	ds_read_b128 v[210:213], v192 offset:54272
	global_load_lds_dwordx4 v168, s[10:11] offset:128
	s_add_i32 m0, s47, 0xffffff80
	ds_read_b128 v[222:225], v192 offset:55296
	global_load_lds_dwordx4 v164, s[10:11] offset:128
	ds_read_b128 v[230:233], v192 offset:56320
	s_waitcnt vmcnt(8)
	s_waitcnt lgkmcnt(0)
	s_barrier
	v_mfma_f32_16x16x32_bf16 v[58:61], v[66:69], v[90:93], v[58:61]
	v_mfma_f32_16x16x32_bf16 v[46:49], v[74:77], v[90:93], v[46:49]
	v_mfma_f32_16x16x32_bf16 v[38:41], v[66:69], v[198:201], v[38:41]
	v_mfma_f32_16x16x32_bf16 v[30:33], v[74:77], v[198:201], v[30:33]
	v_mfma_f32_16x16x32_bf16 v[22:25], v[66:69], v[206:209], v[22:25]
	v_mfma_f32_16x16x32_bf16 v[18:21], v[74:77], v[206:209], v[18:21]
	v_mfma_f32_16x16x32_bf16 v[8:11], v[66:69], v[222:225], v[8:11]
	v_mfma_f32_16x16x32_bf16 v[12:15], v[74:77], v[222:225], v[12:15]
	v_mfma_f32_16x16x32_bf16 v[58:61], v[70:73], v[194:197], v[58:61]
	v_mfma_f32_16x16x32_bf16 v[46:49], v[78:81], v[194:197], v[46:49]
	v_mfma_f32_16x16x32_bf16 v[38:41], v[70:73], v[202:205], v[38:41]
	v_mfma_f32_16x16x32_bf16 v[30:33], v[78:81], v[202:205], v[30:33]
	v_mfma_f32_16x16x32_bf16 v[22:25], v[70:73], v[210:213], v[22:25]
	v_mfma_f32_16x16x32_bf16 v[18:21], v[78:81], v[210:213], v[18:21]
	v_mfma_f32_16x16x32_bf16 v[8:11], v[70:73], v[230:233], v[8:11]
	v_mfma_f32_16x16x32_bf16 v[12:15], v[78:81], v[230:233], v[12:15]
	v_mfma_f32_16x16x32_bf16 v[54:57], v[82:85], v[90:93], v[54:57]
	v_mfma_f32_16x16x32_bf16 v[94:97], v[86:89], v[194:197], v[54:57]
	v_mfma_f32_16x16x32_bf16 v[54:57], v[170:173], v[90:93], v[62:65]
	v_mfma_f32_16x16x32_bf16 v[50:53], v[82:85], v[198:201], v[50:53]
	v_mfma_f32_16x16x32_bf16 v[42:45], v[170:173], v[198:201], v[42:45]
	v_mfma_f32_16x16x32_bf16 v[34:37], v[82:85], v[206:209], v[34:37]
	v_mfma_f32_16x16x32_bf16 v[26:29], v[170:173], v[206:209], v[26:29]
	v_mfma_f32_16x16x32_bf16 v[0:3], v[82:85], v[222:225], v[0:3]
	v_mfma_f32_16x16x32_bf16 v[4:7], v[170:173], v[222:225], v[4:7]
	v_mfma_f32_16x16x32_bf16 v[90:93], v[184:187], v[194:197], v[54:57]
	v_mfma_f32_16x16x32_bf16 v[50:53], v[86:89], v[202:205], v[50:53]
	v_mfma_f32_16x16x32_bf16 v[42:45], v[184:187], v[202:205], v[42:45]
	v_mfma_f32_16x16x32_bf16 v[34:37], v[86:89], v[210:213], v[34:37]
	v_mfma_f32_16x16x32_bf16 v[26:29], v[184:187], v[210:213], v[26:29]
	v_mfma_f32_16x16x32_bf16 v[0:3], v[86:89], v[230:233], v[0:3]
	v_mfma_f32_16x16x32_bf16 v[4:7], v[184:187], v[230:233], v[4:7]
	s_barrier
	s_add_i32 s51, s51, 2
	s_add_u32 s6, s6, 0x100
	s_addc_u32 s7, s7, 0
	s_add_u32 s30, s30, 0x100
	s_addc_u32 s31, s31, 0
	s_cmp_gt_u32 s51, 29
	s_cbranch_scc0 .LBB0_68
	s_and_b64 vcc, exec, s[16:17]
	s_cbranch_vccz .LBB0_71
	s_barrier
